# GEMM K-loops: s_sleep 1 at the start of every slab (chain-sensitivity experiment; the loops turn out throughput-bound and the sleep costs nothing)
# speedup vs baseline: 1.0027x; 1.0027x over previous
; #define MFMA(a, b, c) __builtin_amdgcn_mfma_f32_32x32x16_bf16((a), (b), (c), 0, 0, 0)
; template <bool SWAP, class Epi>
; DI void gemm_tile(const u16* __restrict__ A, int lda, const u16* __restrict__ Bt, int ldb, int K, int m0, int n0, char* smem, Epi&& epi) {
;     ...
;   auto compute = [&](int buf) __attribute__((always_inline)) {
;     bf16x8 af[2][2], bfr[2][2];
;     af[0][0] = *(const bf16x8*)(Asb + buf * 128 * 72);
;     af[0][1] = *(const bf16x8*)(Asb + buf * 128 * 72 + 32 * 72);
;     bfr[0][0] = *(const bf16x8*)(Bsb + buf * 128 * 72);
;     bfr[0][1] = *(const bf16x8*)(Bsb + buf * 128 * 72 + 32 * 72);
; #pragma unroll
;     for (int ks = 0; ks < 4; ++ks) {
;       const int c = ks & 1, n = c ^ 1;
;       if (ks < 3) {
;         af[n][0] = *(const bf16x8*)(Asb + buf * 128 * 72 + (ks + 1) * 16);
;         af[n][1] = *(const bf16x8*)(Asb + buf * 128 * 72 + 32 * 72 + (ks + 1) * 16);
;         bfr[n][0] = *(const bf16x8*)(Bsb + buf * 128 * 72 + (ks + 1) * 16);
;         bfr[n][1] = *(const bf16x8*)(Bsb + buf * 128 * 72 + 32 * 72 + (ks + 1) * 16);
;       }
;       __builtin_amdgcn_sched_barrier(0);
; #pragma unroll
;       for (int mi = 0; mi < 2; ++mi)
; #pragma unroll
;         for (int ni = 0; ni < 2; ++ni) {
;           if (SWAP) acc[mi][ni] = MFMA(bfr[c][ni], af[c][mi], acc[mi][ni]);
;           else acc[mi][ni] = MFMA(af[c][mi], bfr[c][ni], acc[mi][ni]);
;         }
;       __builtin_amdgcn_sched_barrier(0);
;     }
;   };
;   for (int kt = 0; kt < KT; kt += 2) {
;     if (kt + 2 < KT) {
;       const int k0 = (kt + 2) << 6;
; #pragma unroll
;       for (int i = 0; i < 4; ++i) { ra0[i] = *(const u32x4*)(ag + (size_t)i * 32 * lda + k0); rb0[i] = *(const u32x4*)(bg + (size_t)i * 32 * ldb + k0); }
;     }
;     compute(0);
; #pragma unroll
;     for (int i = 0; i < 4; ++i) { *(u32x4*)(asw + 128 * 72 + 32 * i * 72) = ra1[i]; *(u32x4*)(bsw + 128 * 72 + 32 * i * 72) = rb1[i]; }
;     __syncthreads();
;     if (kt + 3 < KT) {
;       const int k0 = (kt + 3) << 6;
; #pragma unroll
;       for (int i = 0; i < 4; ++i) { ra1[i] = *(const u32x4*)(ag + (size_t)i * 32 * lda + k0); rb1[i] = *(const u32x4*)(bg + (size_t)i * 32 * ldb + k0); }
;     }
;     compute(1);
;     if (kt + 2 < KT) {
; #pragma unroll
;       for (int i = 0; i < 4; ++i) { *(u32x4*)(asw + 32 * i * 72) = ra0[i]; *(u32x4*)(bsw + 32 * i * 72) = rb0[i]; }
;     }
;     __syncthreads();
;   }
.LBB0_387:
	s_sleep 1
	global_load_dwordx4 v[66:69], v194, s[100:101] offset:256
	global_load_dwordx4 v[70:73], v190, s[98:99] offset:256
	global_load_dwordx4 v[74:77], v195, s[100:101] offset:256
	global_load_dwordx4 v[78:81], v191, s[98:99] offset:256
	global_load_dwordx4 v[82:85], v196, s[100:101] offset:256
	global_load_dwordx4 v[86:89], v192, s[98:99] offset:256
	global_load_dwordx4 v[90:93], v197, s[100:101] offset:256
	global_load_dwordx4 v[94:97], v193, s[98:99] offset:256
	ds_read_b128 v[170:173], v150 offset:36880
	ds_read_b128 v[154:157], v149 offset:16
	ds_read_b128 v[158:161], v149 offset:2320
	ds_read_b128 v[174:177], v150 offset:39184
	ds_read_b128 v[162:165], v149 offset:4624
	ds_read_b128 v[166:169], v149 offset:6928
	ds_read_b128 v[178:181], v150 offset:41488
	ds_read_b128 v[182:185], v150 offset:43792
	s_waitcnt lgkmcnt(6)
	v_mfma_f32_16x16x32_bf16 v[50:53], v[170:173], v[154:157], v[50:53]
	s_waitcnt lgkmcnt(5)
	v_mfma_f32_16x16x32_bf16 v[54:57], v[170:173], v[158:161], v[54:57]
	s_waitcnt lgkmcnt(4)
	v_mfma_f32_16x16x32_bf16 v[58:61], v[174:177], v[154:157], v[58:61]
	v_mfma_f32_16x16x32_bf16 v[62:65], v[174:177], v[158:161], v[62:65]
	ds_read_b128 v[214:217], v150 offset:36944
	ds_read_b128 v[198:201], v149 offset:80
	ds_read_b128 v[202:205], v149 offset:2384
	ds_read_b128 v[218:221], v150 offset:39248
	s_waitcnt lgkmcnt(7)
	v_mfma_f32_16x16x32_bf16 v[18:21], v[170:173], v[162:165], v[18:21]
	v_mfma_f32_16x16x32_bf16 v[26:29], v[174:177], v[162:165], v[26:29]
	s_waitcnt lgkmcnt(6)
	v_mfma_f32_16x16x32_bf16 v[22:25], v[170:173], v[166:169], v[22:25]
	v_mfma_f32_16x16x32_bf16 v[30:33], v[174:177], v[166:169], v[30:33]
	ds_read_b128 v[206:209], v149 offset:4688
	ds_read_b128 v[210:213], v149 offset:6992
	ds_read_b128 v[222:225], v150 offset:41552
	ds_read_b128 v[226:229], v150 offset:43856
	s_waitcnt lgkmcnt(9)
	v_mfma_f32_16x16x32_bf16 v[34:37], v[178:181], v[154:157], v[34:37]
	v_mfma_f32_16x16x32_bf16 v[38:41], v[178:181], v[158:161], v[38:41]
	v_mfma_f32_16x16x32_bf16 v[2:5], v[178:181], v[162:165], v[2:5]
	v_mfma_f32_16x16x32_bf16 v[6:9], v[178:181], v[166:169], v[6:9]
	s_waitcnt lgkmcnt(8)
	v_mfma_f32_16x16x32_bf16 v[42:45], v[182:185], v[154:157], v[42:45]
	v_mfma_f32_16x16x32_bf16 v[46:49], v[182:185], v[158:161], v[46:49]
	s_waitcnt vmcnt(14)
	ds_write_b128 v146, v[98:101] offset:18448
	ds_write_b128 v146, v[102:105] offset:55312
	v_mfma_f32_16x16x32_bf16 v[10:13], v[182:185], v[162:165], v[10:13]
	v_mfma_f32_16x16x32_bf16 v[14:17], v[182:185], v[166:169], v[14:17]
	s_waitcnt lgkmcnt(8)
	v_mfma_f32_16x16x32_bf16 v[50:53], v[214:217], v[198:201], v[50:53]
	s_waitcnt lgkmcnt(7)
	v_mfma_f32_16x16x32_bf16 v[54:57], v[214:217], v[202:205], v[54:57]
	s_waitcnt vmcnt(12)
	ds_write_b128 v146, v[106:109] offset:23056
	ds_write_b128 v146, v[110:113] offset:59920
	s_waitcnt lgkmcnt(8)
	v_mfma_f32_16x16x32_bf16 v[58:61], v[218:221], v[198:201], v[58:61]
	v_mfma_f32_16x16x32_bf16 v[62:65], v[218:221], v[202:205], v[62:65]
	s_waitcnt lgkmcnt(7)
	v_mfma_f32_16x16x32_bf16 v[18:21], v[214:217], v[206:209], v[18:21]
	v_mfma_f32_16x16x32_bf16 v[26:29], v[218:221], v[206:209], v[26:29]
	s_waitcnt vmcnt(10)
	ds_write_b128 v146, v[114:117] offset:27664
	ds_write_b128 v146, v[118:121] offset:64528
	s_waitcnt lgkmcnt(8)
	v_mfma_f32_16x16x32_bf16 v[22:25], v[214:217], v[210:213], v[22:25]
	v_mfma_f32_16x16x32_bf16 v[30:33], v[218:221], v[210:213], v[30:33]
	s_waitcnt lgkmcnt(7)
	v_mfma_f32_16x16x32_bf16 v[34:37], v[222:225], v[198:201], v[34:37]
	v_mfma_f32_16x16x32_bf16 v[38:41], v[222:225], v[202:205], v[38:41]
	s_waitcnt vmcnt(8)
	ds_write_b128 v146, v[122:125] offset:32272
	ds_write_b128 v147, v[126:129] offset:32256
	v_mfma_f32_16x16x32_bf16 v[2:5], v[222:225], v[206:209], v[2:5]
	v_mfma_f32_16x16x32_bf16 v[6:9], v[222:225], v[210:213], v[6:9]
	s_waitcnt lgkmcnt(8)
	v_mfma_f32_16x16x32_bf16 v[42:45], v[226:229], v[198:201], v[42:45]
	v_mfma_f32_16x16x32_bf16 v[46:49], v[226:229], v[202:205], v[46:49]
	v_mfma_f32_16x16x32_bf16 v[10:13], v[226:229], v[206:209], v[10:13]
	v_mfma_f32_16x16x32_bf16 v[14:17], v[226:229], v[210:213], v[14:17]
	s_waitcnt lgkmcnt(0)
	s_barrier
	s_sleep 1
	global_load_dwordx4 v[98:101], v194, s[100:101] offset:384
	global_load_dwordx4 v[102:105], v190, s[98:99] offset:384
	global_load_dwordx4 v[106:109], v195, s[100:101] offset:384
	global_load_dwordx4 v[110:113], v191, s[98:99] offset:384
	global_load_dwordx4 v[114:117], v196, s[100:101] offset:384
	global_load_dwordx4 v[118:121], v192, s[98:99] offset:384
	global_load_dwordx4 v[122:125], v197, s[100:101] offset:384
	global_load_dwordx4 v[126:129], v193, s[98:99] offset:384
	ds_read_b128 v[170:173], v150 offset:55312
	ds_read_b128 v[154:157], v149 offset:18448
	ds_read_b128 v[158:161], v149 offset:20752
	ds_read_b128 v[174:177], v150 offset:57616
	ds_read_b128 v[162:165], v149 offset:23056
	ds_read_b128 v[166:169], v149 offset:25360
	ds_read_b128 v[178:181], v150 offset:59920
	ds_read_b128 v[182:185], v150 offset:62224
	s_waitcnt lgkmcnt(6)
	v_mfma_f32_16x16x32_bf16 v[50:53], v[170:173], v[154:157], v[50:53]
	s_waitcnt lgkmcnt(5)
	v_mfma_f32_16x16x32_bf16 v[54:57], v[170:173], v[158:161], v[54:57]
	s_waitcnt lgkmcnt(4)
	v_mfma_f32_16x16x32_bf16 v[58:61], v[174:177], v[154:157], v[58:61]
	v_mfma_f32_16x16x32_bf16 v[62:65], v[174:177], v[158:161], v[62:65]
	ds_read_b128 v[214:217], v150 offset:55376
	ds_read_b128 v[198:201], v149 offset:18512
	ds_read_b128 v[202:205], v149 offset:20816
	ds_read_b128 v[218:221], v150 offset:57680
	s_waitcnt lgkmcnt(7)
	v_mfma_f32_16x16x32_bf16 v[18:21], v[170:173], v[162:165], v[18:21]
	v_mfma_f32_16x16x32_bf16 v[26:29], v[174:177], v[162:165], v[26:29]
	s_waitcnt lgkmcnt(6)
; template <bool SWAP, class Epi>
; DI void gemm_tile(const u16* __restrict__ A, int lda, const u16* __restrict__ Bt, int ldb, int K, int m0, int n0, char* smem, Epi&& epi) {
;     ...
;   for (int kt = 0; kt < KT; kt += 2) {
;     if (kt + 2 < KT) {
;       const int k0 = (kt + 2) << 6;
; #pragma unroll
;       for (int i = 0; i < 4; ++i) { ra0[i] = *(const u32x4*)(ag + (size_t)i * 32 * lda + k0); rb0[i] = *(const u32x4*)(bg + (size_t)i * 32 * ldb + k0); }
;     }
;     compute(0);
; #pragma unroll
;     for (int i = 0; i < 4; ++i) { *(u32x4*)(asw + 128 * 72 + 32 * i * 72) = ra1[i]; *(u32x4*)(bsw + 128 * 72 + 32 * i * 72) = rb1[i]; }
;     __syncthreads();
;     if (kt + 3 < KT) {
;       const int k0 = (kt + 3) << 6;
; #pragma unroll
;       for (int i = 0; i < 4; ++i) { ra1[i] = *(const u32x4*)(ag + (size_t)i * 32 * lda + k0); rb1[i] = *(const u32x4*)(bg + (size_t)i * 32 * ldb + k0); }
;     }
;     compute(1);
;     if (kt + 2 < KT) {
; #pragma unroll
;       for (int i = 0; i < 4; ++i) { *(u32x4*)(asw + 32 * i * 72) = ra0[i]; *(u32x4*)(bsw + 32 * i * 72) = rb0[i]; }
;     }
;     __syncthreads();
;   }
	v_mfma_f32_16x16x32_bf16 v[22:25], v[170:173], v[166:169], v[22:25]
	v_mfma_f32_16x16x32_bf16 v[30:33], v[174:177], v[166:169], v[30:33]
	ds_read_b128 v[206:209], v149 offset:23120
	ds_read_b128 v[210:213], v149 offset:25424
	ds_read_b128 v[222:225], v150 offset:59984
	ds_read_b128 v[226:229], v150 offset:62288
	s_waitcnt lgkmcnt(9)
	v_mfma_f32_16x16x32_bf16 v[34:37], v[178:181], v[154:157], v[34:37]
	v_mfma_f32_16x16x32_bf16 v[38:41], v[178:181], v[158:161], v[38:41]
	v_mfma_f32_16x16x32_bf16 v[2:5], v[178:181], v[162:165], v[2:5]
	v_mfma_f32_16x16x32_bf16 v[6:9], v[178:181], v[166:169], v[6:9]
	s_waitcnt lgkmcnt(8)
	v_mfma_f32_16x16x32_bf16 v[42:45], v[182:185], v[154:157], v[42:45]
	v_mfma_f32_16x16x32_bf16 v[46:49], v[182:185], v[158:161], v[46:49]
	s_waitcnt vmcnt(14)
	ds_write_b128 v146, v[66:69] offset:16
	ds_write_b128 v146, v[70:73] offset:36880
	v_mfma_f32_16x16x32_bf16 v[10:13], v[182:185], v[162:165], v[10:13]
	v_mfma_f32_16x16x32_bf16 v[14:17], v[182:185], v[166:169], v[14:17]
	s_waitcnt lgkmcnt(8)
	v_mfma_f32_16x16x32_bf16 v[50:53], v[214:217], v[198:201], v[50:53]
	s_waitcnt lgkmcnt(7)
	v_mfma_f32_16x16x32_bf16 v[54:57], v[214:217], v[202:205], v[54:57]
	s_waitcnt vmcnt(12)
	ds_write_b128 v146, v[74:77] offset:4624
	ds_write_b128 v146, v[78:81] offset:41488
	s_waitcnt lgkmcnt(8)
	v_mfma_f32_16x16x32_bf16 v[58:61], v[218:221], v[198:201], v[58:61]
	v_mfma_f32_16x16x32_bf16 v[62:65], v[218:221], v[202:205], v[62:65]
	s_waitcnt lgkmcnt(7)
	v_mfma_f32_16x16x32_bf16 v[18:21], v[214:217], v[206:209], v[18:21]
	v_mfma_f32_16x16x32_bf16 v[26:29], v[218:221], v[206:209], v[26:29]
	s_waitcnt vmcnt(10)
	ds_write_b128 v146, v[82:85] offset:9232
	ds_write_b128 v146, v[86:89] offset:46096
	s_waitcnt lgkmcnt(8)
	v_mfma_f32_16x16x32_bf16 v[22:25], v[214:217], v[210:213], v[22:25]
	v_mfma_f32_16x16x32_bf16 v[30:33], v[218:221], v[210:213], v[30:33]
	s_waitcnt lgkmcnt(7)
	v_mfma_f32_16x16x32_bf16 v[34:37], v[222:225], v[198:201], v[34:37]
	v_mfma_f32_16x16x32_bf16 v[38:41], v[222:225], v[202:205], v[38:41]
	s_waitcnt vmcnt(8)
	ds_write_b128 v146, v[90:93] offset:13840
	ds_write_b128 v146, v[94:97] offset:50704
	v_mfma_f32_16x16x32_bf16 v[2:5], v[222:225], v[206:209], v[2:5]
	v_mfma_f32_16x16x32_bf16 v[6:9], v[222:225], v[210:213], v[6:9]
	s_waitcnt lgkmcnt(8)
	v_mfma_f32_16x16x32_bf16 v[42:45], v[226:229], v[198:201], v[42:45]
	v_mfma_f32_16x16x32_bf16 v[46:49], v[226:229], v[202:205], v[46:49]
	v_mfma_f32_16x16x32_bf16 v[10:13], v[226:229], v[206:209], v[10:13]
	v_mfma_f32_16x16x32_bf16 v[14:17], v[226:229], v[210:213], v[14:17]
	s_add_i32 s24, s24, 2
	s_add_u32 s98, s98, 256
	s_addc_u32 s99, s99, 0
	s_add_u32 s100, s100, 256
	s_addc_u32 s101, s101, 0
	s_waitcnt lgkmcnt(0)
	s_barrier
	s_cmp_lt_u32 s24, 30
	s_cbranch_scc1 .LBB0_387
	ds_read_b128 v[170:173], v150 offset:36880
	ds_read_b128 v[154:157], v149 offset:16
	ds_read_b128 v[158:161], v149 offset:2320
	ds_read_b128 v[174:177], v150 offset:39184
	ds_read_b128 v[162:165], v149 offset:4624
	ds_read_b128 v[166:169], v149 offset:6928
	ds_read_b128 v[178:181], v150 offset:41488
	ds_read_b128 v[182:185], v150 offset:43792
	s_waitcnt lgkmcnt(6)
	v_mfma_f32_16x16x32_bf16 v[50:53], v[170:173], v[154:157], v[50:53]
	s_waitcnt lgkmcnt(5)
	v_mfma_f32_16x16x32_bf16 v[54:57], v[170:173], v[158:161], v[54:57]
	s_waitcnt lgkmcnt(4)
	v_mfma_f32_16x16x32_bf16 v[58:61], v[174:177], v[154:157], v[58:61]
	v_mfma_f32_16x16x32_bf16 v[62:65], v[174:177], v[158:161], v[62:65]
	ds_read_b128 v[214:217], v150 offset:36944
	ds_read_b128 v[198:201], v149 offset:80
	ds_read_b128 v[202:205], v149 offset:2384
	ds_read_b128 v[218:221], v150 offset:39248
	s_waitcnt lgkmcnt(7)
	v_mfma_f32_16x16x32_bf16 v[18:21], v[170:173], v[162:165], v[18:21]
	v_mfma_f32_16x16x32_bf16 v[26:29], v[174:177], v[162:165], v[26:29]
	s_waitcnt lgkmcnt(6)
	v_mfma_f32_16x16x32_bf16 v[22:25], v[170:173], v[166:169], v[22:25]
	v_mfma_f32_16x16x32_bf16 v[30:33], v[174:177], v[166:169], v[30:33]
	ds_read_b128 v[206:209], v149 offset:4688
	ds_read_b128 v[210:213], v149 offset:6992
	ds_read_b128 v[222:225], v150 offset:41552
	ds_read_b128 v[226:229], v150 offset:43856
	s_waitcnt lgkmcnt(9)
	v_mfma_f32_16x16x32_bf16 v[34:37], v[178:181], v[154:157], v[34:37]
	v_mfma_f32_16x16x32_bf16 v[38:41], v[178:181], v[158:161], v[38:41]
	v_mfma_f32_16x16x32_bf16 v[2:5], v[178:181], v[162:165], v[2:5]
	v_mfma_f32_16x16x32_bf16 v[6:9], v[178:181], v[166:169], v[6:9]
	s_waitcnt lgkmcnt(8)
	v_mfma_f32_16x16x32_bf16 v[42:45], v[182:185], v[154:157], v[42:45]
	v_mfma_f32_16x16x32_bf16 v[46:49], v[182:185], v[158:161], v[46:49]
	s_waitcnt vmcnt(6)
	ds_write_b128 v146, v[98:101] offset:18448
	ds_write_b128 v146, v[102:105] offset:55312
	v_mfma_f32_16x16x32_bf16 v[10:13], v[182:185], v[162:165], v[10:13]
	v_mfma_f32_16x16x32_bf16 v[14:17], v[182:185], v[166:169], v[14:17]
	s_waitcnt lgkmcnt(8)
	v_mfma_f32_16x16x32_bf16 v[50:53], v[214:217], v[198:201], v[50:53]
	s_waitcnt lgkmcnt(7)
	v_mfma_f32_16x16x32_bf16 v[54:57], v[214:217], v[202:205], v[54:57]
	s_waitcnt vmcnt(4)
	ds_write_b128 v146, v[106:109] offset:23056
	ds_write_b128 v146, v[110:113] offset:59920
	s_waitcnt lgkmcnt(8)
	v_mfma_f32_16x16x32_bf16 v[58:61], v[218:221], v[198:201], v[58:61]
	v_mfma_f32_16x16x32_bf16 v[62:65], v[218:221], v[202:205], v[62:65]
	s_waitcnt lgkmcnt(7)
	v_mfma_f32_16x16x32_bf16 v[18:21], v[214:217], v[206:209], v[18:21]
	v_mfma_f32_16x16x32_bf16 v[26:29], v[218:221], v[206:209], v[26:29]
	s_waitcnt vmcnt(2)
	ds_write_b128 v146, v[114:117] offset:27664
	ds_write_b128 v146, v[118:121] offset:64528
	s_waitcnt lgkmcnt(8)
	v_mfma_f32_16x16x32_bf16 v[22:25], v[214:217], v[210:213], v[22:25]
	v_mfma_f32_16x16x32_bf16 v[30:33], v[218:221], v[210:213], v[30:33]
	s_waitcnt lgkmcnt(7)
	v_mfma_f32_16x16x32_bf16 v[34:37], v[222:225], v[198:201], v[34:37]
	v_mfma_f32_16x16x32_bf16 v[38:41], v[222:225], v[202:205], v[38:41]
	s_waitcnt vmcnt(0)
	ds_write_b128 v146, v[122:125] offset:32272
	ds_write_b128 v147, v[126:129] offset:32256
	v_mfma_f32_16x16x32_bf16 v[2:5], v[222:225], v[206:209], v[2:5]
	v_mfma_f32_16x16x32_bf16 v[6:9], v[222:225], v[210:213], v[6:9]
	s_waitcnt lgkmcnt(8)
	v_mfma_f32_16x16x32_bf16 v[42:45], v[226:229], v[198:201], v[42:45]
	v_mfma_f32_16x16x32_bf16 v[46:49], v[226:229], v[202:205], v[46:49]
	v_mfma_f32_16x16x32_bf16 v[10:13], v[226:229], v[206:209], v[10:13]
	v_mfma_f32_16x16x32_bf16 v[14:17], v[226:229], v[210:213], v[14:17]
	s_waitcnt lgkmcnt(0)
	s_barrier
; template <bool SWAP, class Epi>
; DI void gemm_tile(const u16* __restrict__ A, int lda, const u16* __restrict__ Bt, int ldb, int K, int m0, int n0, char* smem, Epi&& epi) {
;     ...
;     compute(1);
;     if (kt + 2 < KT) {
; #pragma unroll
;       for (int i = 0; i < 4; ++i) { *(u32x4*)(asw + 32 * i * 72) = ra0[i]; *(u32x4*)(bsw + 32 * i * 72) = rb0[i]; }
;     }
;     __syncthreads();
;   }
;   epi(acc, m0 + wm * 64, n0 + wn * 64, r, hi);
	ds_read_b128 v[170:173], v150 offset:55312
	ds_read_b128 v[154:157], v149 offset:18448
	ds_read_b128 v[158:161], v149 offset:20752
	ds_read_b128 v[174:177], v150 offset:57616
	ds_read_b128 v[162:165], v149 offset:23056
	ds_read_b128 v[166:169], v149 offset:25360
	ds_read_b128 v[178:181], v150 offset:59920
	ds_read_b128 v[182:185], v150 offset:62224
	s_waitcnt lgkmcnt(6)
	v_mfma_f32_16x16x32_bf16 v[50:53], v[170:173], v[154:157], v[50:53]
	s_waitcnt lgkmcnt(5)
	v_mfma_f32_16x16x32_bf16 v[54:57], v[170:173], v[158:161], v[54:57]
	s_waitcnt lgkmcnt(4)
	v_mfma_f32_16x16x32_bf16 v[58:61], v[174:177], v[154:157], v[58:61]
	v_mfma_f32_16x16x32_bf16 v[62:65], v[174:177], v[158:161], v[62:65]
	ds_read_b128 v[214:217], v150 offset:55376
	ds_read_b128 v[198:201], v149 offset:18512
	ds_read_b128 v[202:205], v149 offset:20816
	ds_read_b128 v[218:221], v150 offset:57680
	s_waitcnt lgkmcnt(7)
	v_mfma_f32_16x16x32_bf16 v[18:21], v[170:173], v[162:165], v[18:21]
	v_mfma_f32_16x16x32_bf16 v[26:29], v[174:177], v[162:165], v[26:29]
	s_waitcnt lgkmcnt(6)
	v_mfma_f32_16x16x32_bf16 v[22:25], v[170:173], v[166:169], v[22:25]
	v_mfma_f32_16x16x32_bf16 v[30:33], v[174:177], v[166:169], v[30:33]
	ds_read_b128 v[206:209], v149 offset:23120
	ds_read_b128 v[210:213], v149 offset:25424
	ds_read_b128 v[222:225], v150 offset:59984
	ds_read_b128 v[226:229], v150 offset:62288
	s_waitcnt lgkmcnt(9)
	v_mfma_f32_16x16x32_bf16 v[34:37], v[178:181], v[154:157], v[34:37]
	v_mfma_f32_16x16x32_bf16 v[38:41], v[178:181], v[158:161], v[38:41]
	v_mfma_f32_16x16x32_bf16 v[2:5], v[178:181], v[162:165], v[2:5]
	v_mfma_f32_16x16x32_bf16 v[6:9], v[178:181], v[166:169], v[6:9]
	s_waitcnt lgkmcnt(8)
	v_mfma_f32_16x16x32_bf16 v[42:45], v[182:185], v[154:157], v[42:45]
	v_mfma_f32_16x16x32_bf16 v[46:49], v[182:185], v[158:161], v[46:49]
	v_mfma_f32_16x16x32_bf16 v[10:13], v[182:185], v[162:165], v[10:13]
	v_mfma_f32_16x16x32_bf16 v[14:17], v[182:185], v[166:169], v[14:17]
	s_waitcnt lgkmcnt(6)
	v_mfma_f32_16x16x32_bf16 v[50:53], v[214:217], v[198:201], v[50:53]
	s_waitcnt lgkmcnt(5)
	v_mfma_f32_16x16x32_bf16 v[54:57], v[214:217], v[202:205], v[54:57]
	s_waitcnt lgkmcnt(4)
	v_mfma_f32_16x16x32_bf16 v[58:61], v[218:221], v[198:201], v[58:61]
	v_mfma_f32_16x16x32_bf16 v[62:65], v[218:221], v[202:205], v[62:65]
	s_waitcnt lgkmcnt(3)
	v_mfma_f32_16x16x32_bf16 v[18:21], v[214:217], v[206:209], v[18:21]
	v_mfma_f32_16x16x32_bf16 v[26:29], v[218:221], v[206:209], v[26:29]
	s_waitcnt lgkmcnt(2)
	v_mfma_f32_16x16x32_bf16 v[22:25], v[214:217], v[210:213], v[22:25]
	v_mfma_f32_16x16x32_bf16 v[30:33], v[218:221], v[210:213], v[30:33]
	s_waitcnt lgkmcnt(1)
	v_mfma_f32_16x16x32_bf16 v[34:37], v[222:225], v[198:201], v[34:37]
	v_mfma_f32_16x16x32_bf16 v[38:41], v[222:225], v[202:205], v[38:41]
	v_mfma_f32_16x16x32_bf16 v[2:5], v[222:225], v[206:209], v[2:5]
	v_mfma_f32_16x16x32_bf16 v[6:9], v[222:225], v[210:213], v[6:9]
	s_waitcnt lgkmcnt(0)
	v_mfma_f32_16x16x32_bf16 v[42:45], v[226:229], v[198:201], v[42:45]
	v_mfma_f32_16x16x32_bf16 v[46:49], v[226:229], v[202:205], v[46:49]
	v_mfma_f32_16x16x32_bf16 v[10:13], v[226:229], v[206:209], v[10:13]
	v_mfma_f32_16x16x32_bf16 v[14:17], v[226:229], v[210:213], v[14:17]
	s_nop 7
	s_nop 7
	v_permlane16_swap_b32_e32 v50, v54
	v_permlane16_swap_b32_e32 v51, v55
	v_permlane16_swap_b32_e32 v52, v56
	v_permlane16_swap_b32_e32 v53, v57
	v_permlane16_swap_b32_e32 v58, v62
	v_permlane16_swap_b32_e32 v59, v63
	v_permlane16_swap_b32_e32 v60, v64
	v_permlane16_swap_b32_e32 v61, v65
	v_permlane16_swap_b32_e32 v34, v38
	v_permlane16_swap_b32_e32 v35, v39
	v_permlane16_swap_b32_e32 v36, v40
	v_permlane16_swap_b32_e32 v37, v41
	v_permlane16_swap_b32_e32 v42, v46
	v_permlane16_swap_b32_e32 v43, v47
	v_permlane16_swap_b32_e32 v44, v48
	v_permlane16_swap_b32_e32 v45, v49
	v_permlane16_swap_b32_e32 v18, v22
	v_permlane16_swap_b32_e32 v19, v23
	v_permlane16_swap_b32_e32 v20, v24
	v_permlane16_swap_b32_e32 v21, v25
	v_permlane16_swap_b32_e32 v26, v30
	v_permlane16_swap_b32_e32 v27, v31
	v_permlane16_swap_b32_e32 v28, v32
	v_permlane16_swap_b32_e32 v29, v33
	v_permlane16_swap_b32_e32 v2, v6
	v_permlane16_swap_b32_e32 v3, v7
	v_permlane16_swap_b32_e32 v4, v8
	v_permlane16_swap_b32_e32 v5, v9
	v_permlane16_swap_b32_e32 v10, v14
	v_permlane16_swap_b32_e32 v11, v15
	v_permlane16_swap_b32_e32 v12, v16
	v_permlane16_swap_b32_e32 v13, v17
	s_waitcnt lgkmcnt(0)
	s_barrier
	s_branch .LBB0_393

; #define MFMA(a, b, c) __builtin_amdgcn_mfma_f32_32x32x16_bf16((a), (b), (c), 0, 0, 0)
; template <bool SWAP, class Epi>
; DI void gemm_tile(const u16* __restrict__ A, int lda, const u16* __restrict__ Bt, int ldb, int K, int m0, int n0, char* smem, Epi&& epi) {
;     ...
;   auto compute = [&](int buf) __attribute__((always_inline)) {
;     bf16x8 af[2][2], bfr[2][2];
;     af[0][0] = *(const bf16x8*)(Asb + buf * 128 * 72);
;     af[0][1] = *(const bf16x8*)(Asb + buf * 128 * 72 + 32 * 72);
;     bfr[0][0] = *(const bf16x8*)(Bsb + buf * 128 * 72);
;     bfr[0][1] = *(const bf16x8*)(Bsb + buf * 128 * 72 + 32 * 72);
; #pragma unroll
;     for (int ks = 0; ks < 4; ++ks) {
;       const int c = ks & 1, n = c ^ 1;
;       if (ks < 3) {
;         af[n][0] = *(const bf16x8*)(Asb + buf * 128 * 72 + (ks + 1) * 16);
;         af[n][1] = *(const bf16x8*)(Asb + buf * 128 * 72 + 32 * 72 + (ks + 1) * 16);
;         bfr[n][0] = *(const bf16x8*)(Bsb + buf * 128 * 72 + (ks + 1) * 16);
;         bfr[n][1] = *(const bf16x8*)(Bsb + buf * 128 * 72 + 32 * 72 + (ks + 1) * 16);
;       }
;       __builtin_amdgcn_sched_barrier(0);
; #pragma unroll
;       for (int mi = 0; mi < 2; ++mi)
; #pragma unroll
;         for (int ni = 0; ni < 2; ++ni) {
;           if (SWAP) acc[mi][ni] = MFMA(bfr[c][ni], af[c][mi], acc[mi][ni]);
;           else acc[mi][ni] = MFMA(af[c][mi], bfr[c][ni], acc[mi][ni]);
;         }
;       __builtin_amdgcn_sched_barrier(0);
;     }
;   };
;   for (int kt = 0; kt < KT; kt += 2) {
;     if (kt + 2 < KT) {
;       const int k0 = (kt + 2) << 6;
; #pragma unroll
;       for (int i = 0; i < 4; ++i) { ra0[i] = *(const u32x4*)(ag + (size_t)i * 32 * lda + k0); rb0[i] = *(const u32x4*)(bg + (size_t)i * 32 * ldb + k0); }
;     }
;     compute(0);
; #pragma unroll
;     for (int i = 0; i < 4; ++i) { *(u32x4*)(asw + 128 * 72 + 32 * i * 72) = ra1[i]; *(u32x4*)(bsw + 128 * 72 + 32 * i * 72) = rb1[i]; }
;     __syncthreads();
;     if (kt + 3 < KT) {
;       const int k0 = (kt + 3) << 6;
; #pragma unroll
;       for (int i = 0; i < 4; ++i) { ra1[i] = *(const u32x4*)(ag + (size_t)i * 32 * lda + k0); rb1[i] = *(const u32x4*)(bg + (size_t)i * 32 * ldb + k0); }
;     }
;     compute(1);
;     if (kt + 2 < KT) {
; #pragma unroll
;       for (int i = 0; i < 4; ++i) { *(u32x4*)(asw + 32 * i * 72) = ra0[i]; *(u32x4*)(bsw + 32 * i * 72) = rb0[i]; }
;     }
;     __syncthreads();
;   }
.LBB0_748:
	s_sleep 1
	global_load_dwordx4 v[66:69], v194, s[100:101] offset:256
	global_load_dwordx4 v[70:73], v190, s[98:99] offset:256
	global_load_dwordx4 v[74:77], v195, s[100:101] offset:256
	global_load_dwordx4 v[78:81], v191, s[98:99] offset:256
	global_load_dwordx4 v[82:85], v196, s[100:101] offset:256
	global_load_dwordx4 v[86:89], v192, s[98:99] offset:256
	global_load_dwordx4 v[90:93], v197, s[100:101] offset:256
	global_load_dwordx4 v[94:97], v193, s[98:99] offset:256
	ds_read_b128 v[166:169], v148 offset:36880
	ds_read_b128 v[150:153], v147 offset:16
	ds_read_b128 v[154:157], v147 offset:2320
	ds_read_b128 v[170:173], v148 offset:39184
	ds_read_b128 v[158:161], v147 offset:4624
	ds_read_b128 v[162:165], v147 offset:6928
	ds_read_b128 v[174:177], v148 offset:41488
	ds_read_b128 v[178:181], v148 offset:43792
	s_waitcnt lgkmcnt(6)
	v_mfma_f32_16x16x32_bf16 v[50:53], v[166:169], v[150:153], v[50:53]
	s_waitcnt lgkmcnt(5)
	v_mfma_f32_16x16x32_bf16 v[54:57], v[166:169], v[154:157], v[54:57]
	s_waitcnt lgkmcnt(4)
	v_mfma_f32_16x16x32_bf16 v[58:61], v[170:173], v[150:153], v[58:61]
	v_mfma_f32_16x16x32_bf16 v[62:65], v[170:173], v[154:157], v[62:65]
	ds_read_b128 v[214:217], v148 offset:36944
	ds_read_b128 v[198:201], v147 offset:80
	ds_read_b128 v[202:205], v147 offset:2384
	ds_read_b128 v[218:221], v148 offset:39248
	s_waitcnt lgkmcnt(7)
	v_mfma_f32_16x16x32_bf16 v[18:21], v[166:169], v[158:161], v[18:21]
	v_mfma_f32_16x16x32_bf16 v[26:29], v[170:173], v[158:161], v[26:29]
	s_waitcnt lgkmcnt(6)
	v_mfma_f32_16x16x32_bf16 v[22:25], v[166:169], v[162:165], v[22:25]
	v_mfma_f32_16x16x32_bf16 v[30:33], v[170:173], v[162:165], v[30:33]
	ds_read_b128 v[206:209], v147 offset:4688
	ds_read_b128 v[210:213], v147 offset:6992
	ds_read_b128 v[222:225], v148 offset:41552
	ds_read_b128 v[226:229], v148 offset:43856
	s_waitcnt lgkmcnt(9)
	v_mfma_f32_16x16x32_bf16 v[34:37], v[174:177], v[150:153], v[34:37]
	v_mfma_f32_16x16x32_bf16 v[38:41], v[174:177], v[154:157], v[38:41]
	v_mfma_f32_16x16x32_bf16 v[2:5], v[174:177], v[158:161], v[2:5]
	v_mfma_f32_16x16x32_bf16 v[6:9], v[174:177], v[162:165], v[6:9]
	s_waitcnt lgkmcnt(8)
	v_mfma_f32_16x16x32_bf16 v[42:45], v[178:181], v[150:153], v[42:45]
	v_mfma_f32_16x16x32_bf16 v[46:49], v[178:181], v[154:157], v[46:49]
	s_waitcnt vmcnt(14)
	ds_write_b128 v144, v[98:101] offset:18448
	ds_write_b128 v144, v[102:105] offset:55312
	v_mfma_f32_16x16x32_bf16 v[10:13], v[178:181], v[158:161], v[10:13]
	v_mfma_f32_16x16x32_bf16 v[14:17], v[178:181], v[162:165], v[14:17]
	s_waitcnt lgkmcnt(8)
	v_mfma_f32_16x16x32_bf16 v[50:53], v[214:217], v[198:201], v[50:53]
	s_waitcnt lgkmcnt(7)
	v_mfma_f32_16x16x32_bf16 v[54:57], v[214:217], v[202:205], v[54:57]
	s_waitcnt vmcnt(12)
	ds_write_b128 v144, v[106:109] offset:23056
	ds_write_b128 v144, v[110:113] offset:59920
	s_waitcnt lgkmcnt(8)
	v_mfma_f32_16x16x32_bf16 v[58:61], v[218:221], v[198:201], v[58:61]
	v_mfma_f32_16x16x32_bf16 v[62:65], v[218:221], v[202:205], v[62:65]
	s_waitcnt lgkmcnt(7)
	v_mfma_f32_16x16x32_bf16 v[18:21], v[214:217], v[206:209], v[18:21]
	v_mfma_f32_16x16x32_bf16 v[26:29], v[218:221], v[206:209], v[26:29]
	s_waitcnt vmcnt(10)
	ds_write_b128 v144, v[114:117] offset:27664
	ds_write_b128 v144, v[118:121] offset:64528
	s_waitcnt lgkmcnt(8)
	v_mfma_f32_16x16x32_bf16 v[22:25], v[214:217], v[210:213], v[22:25]
	v_mfma_f32_16x16x32_bf16 v[30:33], v[218:221], v[210:213], v[30:33]
	s_waitcnt lgkmcnt(7)
	v_mfma_f32_16x16x32_bf16 v[34:37], v[222:225], v[198:201], v[34:37]
	v_mfma_f32_16x16x32_bf16 v[38:41], v[222:225], v[202:205], v[38:41]
	s_waitcnt vmcnt(8)
	ds_write_b128 v144, v[122:125] offset:32272
	ds_write_b128 v145, v[126:129] offset:32256
	v_mfma_f32_16x16x32_bf16 v[2:5], v[222:225], v[206:209], v[2:5]
	v_mfma_f32_16x16x32_bf16 v[6:9], v[222:225], v[210:213], v[6:9]
	s_waitcnt lgkmcnt(8)
	v_mfma_f32_16x16x32_bf16 v[42:45], v[226:229], v[198:201], v[42:45]
	v_mfma_f32_16x16x32_bf16 v[46:49], v[226:229], v[202:205], v[46:49]
	v_mfma_f32_16x16x32_bf16 v[10:13], v[226:229], v[206:209], v[10:13]
	v_mfma_f32_16x16x32_bf16 v[14:17], v[226:229], v[210:213], v[14:17]
	s_waitcnt lgkmcnt(0)
	s_barrier
	s_sleep 1
	global_load_dwordx4 v[98:101], v194, s[100:101] offset:384
	global_load_dwordx4 v[102:105], v190, s[98:99] offset:384
	global_load_dwordx4 v[106:109], v195, s[100:101] offset:384
	global_load_dwordx4 v[110:113], v191, s[98:99] offset:384
	global_load_dwordx4 v[114:117], v196, s[100:101] offset:384
	global_load_dwordx4 v[118:121], v192, s[98:99] offset:384
	global_load_dwordx4 v[122:125], v197, s[100:101] offset:384
	global_load_dwordx4 v[126:129], v193, s[98:99] offset:384
	ds_read_b128 v[166:169], v148 offset:55312
	ds_read_b128 v[150:153], v147 offset:18448
	ds_read_b128 v[154:157], v147 offset:20752
	ds_read_b128 v[170:173], v148 offset:57616
	ds_read_b128 v[158:161], v147 offset:23056
	ds_read_b128 v[162:165], v147 offset:25360
	ds_read_b128 v[174:177], v148 offset:59920
	ds_read_b128 v[178:181], v148 offset:62224
	s_waitcnt lgkmcnt(6)
	v_mfma_f32_16x16x32_bf16 v[50:53], v[166:169], v[150:153], v[50:53]
	s_waitcnt lgkmcnt(5)
	v_mfma_f32_16x16x32_bf16 v[54:57], v[166:169], v[154:157], v[54:57]
	s_waitcnt lgkmcnt(4)
	v_mfma_f32_16x16x32_bf16 v[58:61], v[170:173], v[150:153], v[58:61]
	v_mfma_f32_16x16x32_bf16 v[62:65], v[170:173], v[154:157], v[62:65]
	ds_read_b128 v[214:217], v148 offset:55376
	ds_read_b128 v[198:201], v147 offset:18512
	ds_read_b128 v[202:205], v147 offset:20816
	ds_read_b128 v[218:221], v148 offset:57680
	s_waitcnt lgkmcnt(7)
	v_mfma_f32_16x16x32_bf16 v[18:21], v[166:169], v[158:161], v[18:21]
	v_mfma_f32_16x16x32_bf16 v[26:29], v[170:173], v[158:161], v[26:29]
	s_waitcnt lgkmcnt(6)
; template <bool SWAP, class Epi>
; DI void gemm_tile(const u16* __restrict__ A, int lda, const u16* __restrict__ Bt, int ldb, int K, int m0, int n0, char* smem, Epi&& epi) {
;     ...
;   for (int kt = 0; kt < KT; kt += 2) {
;     if (kt + 2 < KT) {
;       const int k0 = (kt + 2) << 6;
; #pragma unroll
;       for (int i = 0; i < 4; ++i) { ra0[i] = *(const u32x4*)(ag + (size_t)i * 32 * lda + k0); rb0[i] = *(const u32x4*)(bg + (size_t)i * 32 * ldb + k0); }
;     }
;     compute(0);
; #pragma unroll
;     for (int i = 0; i < 4; ++i) { *(u32x4*)(asw + 128 * 72 + 32 * i * 72) = ra1[i]; *(u32x4*)(bsw + 128 * 72 + 32 * i * 72) = rb1[i]; }
;     __syncthreads();
;     if (kt + 3 < KT) {
;       const int k0 = (kt + 3) << 6;
; #pragma unroll
;       for (int i = 0; i < 4; ++i) { ra1[i] = *(const u32x4*)(ag + (size_t)i * 32 * lda + k0); rb1[i] = *(const u32x4*)(bg + (size_t)i * 32 * ldb + k0); }
;     }
;     compute(1);
;     if (kt + 2 < KT) {
; #pragma unroll
;       for (int i = 0; i < 4; ++i) { *(u32x4*)(asw + 32 * i * 72) = ra0[i]; *(u32x4*)(bsw + 32 * i * 72) = rb0[i]; }
;     }
;     __syncthreads();
;   }
	v_mfma_f32_16x16x32_bf16 v[22:25], v[166:169], v[162:165], v[22:25]
	v_mfma_f32_16x16x32_bf16 v[30:33], v[170:173], v[162:165], v[30:33]
	ds_read_b128 v[206:209], v147 offset:23120
	ds_read_b128 v[210:213], v147 offset:25424
	ds_read_b128 v[222:225], v148 offset:59984
	ds_read_b128 v[226:229], v148 offset:62288
	s_waitcnt lgkmcnt(9)
	v_mfma_f32_16x16x32_bf16 v[34:37], v[174:177], v[150:153], v[34:37]
	v_mfma_f32_16x16x32_bf16 v[38:41], v[174:177], v[154:157], v[38:41]
	v_mfma_f32_16x16x32_bf16 v[2:5], v[174:177], v[158:161], v[2:5]
	v_mfma_f32_16x16x32_bf16 v[6:9], v[174:177], v[162:165], v[6:9]
	s_waitcnt lgkmcnt(8)
	v_mfma_f32_16x16x32_bf16 v[42:45], v[178:181], v[150:153], v[42:45]
	v_mfma_f32_16x16x32_bf16 v[46:49], v[178:181], v[154:157], v[46:49]
	s_waitcnt vmcnt(14)
	ds_write_b128 v144, v[66:69] offset:16
	ds_write_b128 v144, v[70:73] offset:36880
	v_mfma_f32_16x16x32_bf16 v[10:13], v[178:181], v[158:161], v[10:13]
	v_mfma_f32_16x16x32_bf16 v[14:17], v[178:181], v[162:165], v[14:17]
	s_waitcnt lgkmcnt(8)
	v_mfma_f32_16x16x32_bf16 v[50:53], v[214:217], v[198:201], v[50:53]
	s_waitcnt lgkmcnt(7)
	v_mfma_f32_16x16x32_bf16 v[54:57], v[214:217], v[202:205], v[54:57]
	s_waitcnt vmcnt(12)
	ds_write_b128 v144, v[74:77] offset:4624
	ds_write_b128 v144, v[78:81] offset:41488
	s_waitcnt lgkmcnt(8)
	v_mfma_f32_16x16x32_bf16 v[58:61], v[218:221], v[198:201], v[58:61]
	v_mfma_f32_16x16x32_bf16 v[62:65], v[218:221], v[202:205], v[62:65]
	s_waitcnt lgkmcnt(7)
	v_mfma_f32_16x16x32_bf16 v[18:21], v[214:217], v[206:209], v[18:21]
	v_mfma_f32_16x16x32_bf16 v[26:29], v[218:221], v[206:209], v[26:29]
	s_waitcnt vmcnt(10)
	ds_write_b128 v144, v[82:85] offset:9232
	ds_write_b128 v144, v[86:89] offset:46096
	s_waitcnt lgkmcnt(8)
	v_mfma_f32_16x16x32_bf16 v[22:25], v[214:217], v[210:213], v[22:25]
	v_mfma_f32_16x16x32_bf16 v[30:33], v[218:221], v[210:213], v[30:33]
	s_waitcnt lgkmcnt(7)
	v_mfma_f32_16x16x32_bf16 v[34:37], v[222:225], v[198:201], v[34:37]
	v_mfma_f32_16x16x32_bf16 v[38:41], v[222:225], v[202:205], v[38:41]
	s_waitcnt vmcnt(8)
	ds_write_b128 v144, v[90:93] offset:13840
	ds_write_b128 v144, v[94:97] offset:50704
	v_mfma_f32_16x16x32_bf16 v[2:5], v[222:225], v[206:209], v[2:5]
	v_mfma_f32_16x16x32_bf16 v[6:9], v[222:225], v[210:213], v[6:9]
	s_waitcnt lgkmcnt(8)
	v_mfma_f32_16x16x32_bf16 v[42:45], v[226:229], v[198:201], v[42:45]
	v_mfma_f32_16x16x32_bf16 v[46:49], v[226:229], v[202:205], v[46:49]
	v_mfma_f32_16x16x32_bf16 v[10:13], v[226:229], v[206:209], v[10:13]
	v_mfma_f32_16x16x32_bf16 v[14:17], v[226:229], v[210:213], v[14:17]
	s_add_i32 s20, s20, 2
	s_add_u32 s98, s98, 256
	s_addc_u32 s99, s99, 0
	s_add_u32 s100, s100, 256
	s_addc_u32 s101, s101, 0
	s_waitcnt lgkmcnt(0)
	s_barrier
	s_cmp_lt_u32 s20, 30
	s_cbranch_scc1 .LBB0_748
	ds_read_b128 v[166:169], v148 offset:36880
	ds_read_b128 v[150:153], v147 offset:16
	ds_read_b128 v[154:157], v147 offset:2320
	ds_read_b128 v[170:173], v148 offset:39184
	ds_read_b128 v[158:161], v147 offset:4624
	ds_read_b128 v[162:165], v147 offset:6928
	ds_read_b128 v[174:177], v148 offset:41488
	ds_read_b128 v[178:181], v148 offset:43792
	s_waitcnt lgkmcnt(6)
	v_mfma_f32_16x16x32_bf16 v[50:53], v[166:169], v[150:153], v[50:53]
	s_waitcnt lgkmcnt(5)
	v_mfma_f32_16x16x32_bf16 v[54:57], v[166:169], v[154:157], v[54:57]
	s_waitcnt lgkmcnt(4)
	v_mfma_f32_16x16x32_bf16 v[58:61], v[170:173], v[150:153], v[58:61]
	v_mfma_f32_16x16x32_bf16 v[62:65], v[170:173], v[154:157], v[62:65]
	ds_read_b128 v[214:217], v148 offset:36944
	ds_read_b128 v[198:201], v147 offset:80
	ds_read_b128 v[202:205], v147 offset:2384
	ds_read_b128 v[218:221], v148 offset:39248
	s_waitcnt lgkmcnt(7)
	v_mfma_f32_16x16x32_bf16 v[18:21], v[166:169], v[158:161], v[18:21]
	v_mfma_f32_16x16x32_bf16 v[26:29], v[170:173], v[158:161], v[26:29]
	s_waitcnt lgkmcnt(6)
	v_mfma_f32_16x16x32_bf16 v[22:25], v[166:169], v[162:165], v[22:25]
	v_mfma_f32_16x16x32_bf16 v[30:33], v[170:173], v[162:165], v[30:33]
	ds_read_b128 v[206:209], v147 offset:4688
	ds_read_b128 v[210:213], v147 offset:6992
	ds_read_b128 v[222:225], v148 offset:41552
	ds_read_b128 v[226:229], v148 offset:43856
	s_waitcnt lgkmcnt(9)
	v_mfma_f32_16x16x32_bf16 v[34:37], v[174:177], v[150:153], v[34:37]
	v_mfma_f32_16x16x32_bf16 v[38:41], v[174:177], v[154:157], v[38:41]
	v_mfma_f32_16x16x32_bf16 v[2:5], v[174:177], v[158:161], v[2:5]
	v_mfma_f32_16x16x32_bf16 v[6:9], v[174:177], v[162:165], v[6:9]
	s_waitcnt lgkmcnt(8)
	v_mfma_f32_16x16x32_bf16 v[42:45], v[178:181], v[150:153], v[42:45]
	v_mfma_f32_16x16x32_bf16 v[46:49], v[178:181], v[154:157], v[46:49]
	s_waitcnt vmcnt(6)
	ds_write_b128 v144, v[98:101] offset:18448
	ds_write_b128 v144, v[102:105] offset:55312
	v_mfma_f32_16x16x32_bf16 v[10:13], v[178:181], v[158:161], v[10:13]
	v_mfma_f32_16x16x32_bf16 v[14:17], v[178:181], v[162:165], v[14:17]
	s_waitcnt lgkmcnt(8)
	v_mfma_f32_16x16x32_bf16 v[50:53], v[214:217], v[198:201], v[50:53]
	s_waitcnt lgkmcnt(7)
	v_mfma_f32_16x16x32_bf16 v[54:57], v[214:217], v[202:205], v[54:57]
	s_waitcnt vmcnt(4)
	ds_write_b128 v144, v[106:109] offset:23056
	ds_write_b128 v144, v[110:113] offset:59920
	s_waitcnt lgkmcnt(8)
	v_mfma_f32_16x16x32_bf16 v[58:61], v[218:221], v[198:201], v[58:61]
	v_mfma_f32_16x16x32_bf16 v[62:65], v[218:221], v[202:205], v[62:65]
	s_waitcnt lgkmcnt(7)
	v_mfma_f32_16x16x32_bf16 v[18:21], v[214:217], v[206:209], v[18:21]
	v_mfma_f32_16x16x32_bf16 v[26:29], v[218:221], v[206:209], v[26:29]
	s_waitcnt vmcnt(2)
	ds_write_b128 v144, v[114:117] offset:27664
	ds_write_b128 v144, v[118:121] offset:64528
	s_waitcnt lgkmcnt(8)
	v_mfma_f32_16x16x32_bf16 v[22:25], v[214:217], v[210:213], v[22:25]
	v_mfma_f32_16x16x32_bf16 v[30:33], v[218:221], v[210:213], v[30:33]
	s_waitcnt lgkmcnt(7)
	v_mfma_f32_16x16x32_bf16 v[34:37], v[222:225], v[198:201], v[34:37]
	v_mfma_f32_16x16x32_bf16 v[38:41], v[222:225], v[202:205], v[38:41]
	s_waitcnt vmcnt(0)
	ds_write_b128 v144, v[122:125] offset:32272
	ds_write_b128 v145, v[126:129] offset:32256
	v_mfma_f32_16x16x32_bf16 v[2:5], v[222:225], v[206:209], v[2:5]
	v_mfma_f32_16x16x32_bf16 v[6:9], v[222:225], v[210:213], v[6:9]
	s_waitcnt lgkmcnt(8)
	v_mfma_f32_16x16x32_bf16 v[42:45], v[226:229], v[198:201], v[42:45]
	v_mfma_f32_16x16x32_bf16 v[46:49], v[226:229], v[202:205], v[46:49]
	v_mfma_f32_16x16x32_bf16 v[10:13], v[226:229], v[206:209], v[10:13]
	v_mfma_f32_16x16x32_bf16 v[14:17], v[226:229], v[210:213], v[14:17]
	s_waitcnt lgkmcnt(0)
	s_barrier
; template <bool SWAP, class Epi>
; DI void gemm_tile(const u16* __restrict__ A, int lda, const u16* __restrict__ Bt, int ldb, int K, int m0, int n0, char* smem, Epi&& epi) {
;     ...
;     compute(1);
;     if (kt + 2 < KT) {
; #pragma unroll
;       for (int i = 0; i < 4; ++i) { *(u32x4*)(asw + 32 * i * 72) = ra0[i]; *(u32x4*)(bsw + 32 * i * 72) = rb0[i]; }
;     }
;     __syncthreads();
;   }
;   epi(acc, m0 + wm * 64, n0 + wn * 64, r, hi);
	ds_read_b128 v[166:169], v148 offset:55312
	ds_read_b128 v[150:153], v147 offset:18448
	ds_read_b128 v[154:157], v147 offset:20752
	ds_read_b128 v[170:173], v148 offset:57616
	ds_read_b128 v[158:161], v147 offset:23056
	ds_read_b128 v[162:165], v147 offset:25360
	ds_read_b128 v[174:177], v148 offset:59920
	ds_read_b128 v[178:181], v148 offset:62224
	s_waitcnt lgkmcnt(6)
	v_mfma_f32_16x16x32_bf16 v[50:53], v[166:169], v[150:153], v[50:53]
	s_waitcnt lgkmcnt(5)
	v_mfma_f32_16x16x32_bf16 v[54:57], v[166:169], v[154:157], v[54:57]
	s_waitcnt lgkmcnt(4)
	v_mfma_f32_16x16x32_bf16 v[58:61], v[170:173], v[150:153], v[58:61]
	v_mfma_f32_16x16x32_bf16 v[62:65], v[170:173], v[154:157], v[62:65]
	ds_read_b128 v[214:217], v148 offset:55376
	ds_read_b128 v[198:201], v147 offset:18512
	ds_read_b128 v[202:205], v147 offset:20816
	ds_read_b128 v[218:221], v148 offset:57680
	s_waitcnt lgkmcnt(7)
	v_mfma_f32_16x16x32_bf16 v[18:21], v[166:169], v[158:161], v[18:21]
	v_mfma_f32_16x16x32_bf16 v[26:29], v[170:173], v[158:161], v[26:29]
	s_waitcnt lgkmcnt(6)
	v_mfma_f32_16x16x32_bf16 v[22:25], v[166:169], v[162:165], v[22:25]
	v_mfma_f32_16x16x32_bf16 v[30:33], v[170:173], v[162:165], v[30:33]
	ds_read_b128 v[206:209], v147 offset:23120
	ds_read_b128 v[210:213], v147 offset:25424
	ds_read_b128 v[222:225], v148 offset:59984
	ds_read_b128 v[226:229], v148 offset:62288
	s_waitcnt lgkmcnt(9)
	v_mfma_f32_16x16x32_bf16 v[34:37], v[174:177], v[150:153], v[34:37]
	v_mfma_f32_16x16x32_bf16 v[38:41], v[174:177], v[154:157], v[38:41]
	v_mfma_f32_16x16x32_bf16 v[2:5], v[174:177], v[158:161], v[2:5]
	v_mfma_f32_16x16x32_bf16 v[6:9], v[174:177], v[162:165], v[6:9]
	s_waitcnt lgkmcnt(8)
	v_mfma_f32_16x16x32_bf16 v[42:45], v[178:181], v[150:153], v[42:45]
	v_mfma_f32_16x16x32_bf16 v[46:49], v[178:181], v[154:157], v[46:49]
	v_mfma_f32_16x16x32_bf16 v[10:13], v[178:181], v[158:161], v[10:13]
	v_mfma_f32_16x16x32_bf16 v[14:17], v[178:181], v[162:165], v[14:17]
	s_waitcnt lgkmcnt(6)
	v_mfma_f32_16x16x32_bf16 v[50:53], v[214:217], v[198:201], v[50:53]
	s_waitcnt lgkmcnt(5)
	v_mfma_f32_16x16x32_bf16 v[54:57], v[214:217], v[202:205], v[54:57]
	s_waitcnt lgkmcnt(4)
	v_mfma_f32_16x16x32_bf16 v[58:61], v[218:221], v[198:201], v[58:61]
	v_mfma_f32_16x16x32_bf16 v[62:65], v[218:221], v[202:205], v[62:65]
	s_waitcnt lgkmcnt(3)
	v_mfma_f32_16x16x32_bf16 v[18:21], v[214:217], v[206:209], v[18:21]
	v_mfma_f32_16x16x32_bf16 v[26:29], v[218:221], v[206:209], v[26:29]
	s_waitcnt lgkmcnt(2)
	v_mfma_f32_16x16x32_bf16 v[22:25], v[214:217], v[210:213], v[22:25]
	v_mfma_f32_16x16x32_bf16 v[30:33], v[218:221], v[210:213], v[30:33]
	s_waitcnt lgkmcnt(1)
	v_mfma_f32_16x16x32_bf16 v[34:37], v[222:225], v[198:201], v[34:37]
	v_mfma_f32_16x16x32_bf16 v[38:41], v[222:225], v[202:205], v[38:41]
	v_mfma_f32_16x16x32_bf16 v[2:5], v[222:225], v[206:209], v[2:5]
	v_mfma_f32_16x16x32_bf16 v[6:9], v[222:225], v[210:213], v[6:9]
	s_waitcnt lgkmcnt(0)
	v_mfma_f32_16x16x32_bf16 v[42:45], v[226:229], v[198:201], v[42:45]
	v_mfma_f32_16x16x32_bf16 v[46:49], v[226:229], v[202:205], v[46:49]
	v_mfma_f32_16x16x32_bf16 v[10:13], v[226:229], v[206:209], v[10:13]
	v_mfma_f32_16x16x32_bf16 v[14:17], v[226:229], v[210:213], v[14:17]
	s_nop 7
	s_nop 7
	v_permlane16_swap_b32_e32 v50, v54
	v_permlane16_swap_b32_e32 v51, v55
	v_permlane16_swap_b32_e32 v52, v56
	v_permlane16_swap_b32_e32 v53, v57
	v_permlane16_swap_b32_e32 v58, v62
	v_permlane16_swap_b32_e32 v59, v63
	v_permlane16_swap_b32_e32 v60, v64
	v_permlane16_swap_b32_e32 v61, v65
	v_permlane16_swap_b32_e32 v34, v38
	v_permlane16_swap_b32_e32 v35, v39
	v_permlane16_swap_b32_e32 v36, v40
	v_permlane16_swap_b32_e32 v37, v41
	v_permlane16_swap_b32_e32 v42, v46
	v_permlane16_swap_b32_e32 v43, v47
	v_permlane16_swap_b32_e32 v44, v48
	v_permlane16_swap_b32_e32 v45, v49
	v_permlane16_swap_b32_e32 v18, v22
	v_permlane16_swap_b32_e32 v19, v23
	v_permlane16_swap_b32_e32 v20, v24
	v_permlane16_swap_b32_e32 v21, v25
	v_permlane16_swap_b32_e32 v26, v30
	v_permlane16_swap_b32_e32 v27, v31
	v_permlane16_swap_b32_e32 v28, v32
	v_permlane16_swap_b32_e32 v29, v33
	v_permlane16_swap_b32_e32 v2, v6
	v_permlane16_swap_b32_e32 v3, v7
	v_permlane16_swap_b32_e32 v4, v8
	v_permlane16_swap_b32_e32 v5, v9
	v_permlane16_swap_b32_e32 v10, v14
	v_permlane16_swap_b32_e32 v11, v15
	v_permlane16_swap_b32_e32 v12, v16
	v_permlane16_swap_b32_e32 v13, v17
	s_waitcnt lgkmcnt(0)
	s_barrier
	s_branch .LBB0_745

; #define MFMA(a, b, c) __builtin_amdgcn_mfma_f32_32x32x16_bf16((a), (b), (c), 0, 0, 0)
; template <bool SWAP, class Epi>
; DI void gemm_tile(const u16* __restrict__ A, int lda, const u16* __restrict__ Bt, int ldb, int K, int m0, int n0, char* smem, Epi&& epi) {
;     ...
;   auto compute = [&](int buf) __attribute__((always_inline)) {
;     bf16x8 af[2][2], bfr[2][2];
;     af[0][0] = *(const bf16x8*)(Asb + buf * 128 * 72);
;     af[0][1] = *(const bf16x8*)(Asb + buf * 128 * 72 + 32 * 72);
;     bfr[0][0] = *(const bf16x8*)(Bsb + buf * 128 * 72);
;     bfr[0][1] = *(const bf16x8*)(Bsb + buf * 128 * 72 + 32 * 72);
; #pragma unroll
;     for (int ks = 0; ks < 4; ++ks) {
;       const int c = ks & 1, n = c ^ 1;
;       if (ks < 3) {
;         af[n][0] = *(const bf16x8*)(Asb + buf * 128 * 72 + (ks + 1) * 16);
;         af[n][1] = *(const bf16x8*)(Asb + buf * 128 * 72 + 32 * 72 + (ks + 1) * 16);
;         bfr[n][0] = *(const bf16x8*)(Bsb + buf * 128 * 72 + (ks + 1) * 16);
;         bfr[n][1] = *(const bf16x8*)(Bsb + buf * 128 * 72 + 32 * 72 + (ks + 1) * 16);
;       }
;       __builtin_amdgcn_sched_barrier(0);
; #pragma unroll
;       for (int mi = 0; mi < 2; ++mi)
; #pragma unroll
;         for (int ni = 0; ni < 2; ++ni) {
;           if (SWAP) acc[mi][ni] = MFMA(bfr[c][ni], af[c][mi], acc[mi][ni]);
;           else acc[mi][ni] = MFMA(af[c][mi], bfr[c][ni], acc[mi][ni]);
;         }
;       __builtin_amdgcn_sched_barrier(0);
;     }
;   };
;   for (int kt = 0; kt < KT; kt += 2) {
;     if (kt + 2 < KT) {
;       const int k0 = (kt + 2) << 6;
; #pragma unroll
;       for (int i = 0; i < 4; ++i) { ra0[i] = *(const u32x4*)(ag + (size_t)i * 32 * lda + k0); rb0[i] = *(const u32x4*)(bg + (size_t)i * 32 * ldb + k0); }
;     }
;     compute(0);
; #pragma unroll
;     for (int i = 0; i < 4; ++i) { *(u32x4*)(asw + 128 * 72 + 32 * i * 72) = ra1[i]; *(u32x4*)(bsw + 128 * 72 + 32 * i * 72) = rb1[i]; }
;     __syncthreads();
;     if (kt + 3 < KT) {
;       const int k0 = (kt + 3) << 6;
; #pragma unroll
;       for (int i = 0; i < 4; ++i) { ra1[i] = *(const u32x4*)(ag + (size_t)i * 32 * lda + k0); rb1[i] = *(const u32x4*)(bg + (size_t)i * 32 * ldb + k0); }
;     }
;     compute(1);
;     if (kt + 2 < KT) {
; #pragma unroll
;       for (int i = 0; i < 4; ++i) { *(u32x4*)(asw + 32 * i * 72) = ra0[i]; *(u32x4*)(bsw + 32 * i * 72) = rb0[i]; }
;     }
;     __syncthreads();
;   }
.LBB0_955:
	s_sleep 1
	global_load_dwordx4 v[66:69], v194, s[100:101] offset:256
	global_load_dwordx4 v[70:73], v190, s[98:99] offset:256
	global_load_dwordx4 v[74:77], v195, s[100:101] offset:256
	global_load_dwordx4 v[78:81], v191, s[98:99] offset:256
	global_load_dwordx4 v[82:85], v196, s[100:101] offset:256
	global_load_dwordx4 v[86:89], v192, s[98:99] offset:256
	global_load_dwordx4 v[90:93], v197, s[100:101] offset:256
	global_load_dwordx4 v[94:97], v193, s[98:99] offset:256
	ds_read_b128 v[166:169], v148 offset:36880
	ds_read_b128 v[150:153], v147 offset:16
	ds_read_b128 v[154:157], v147 offset:2320
	ds_read_b128 v[170:173], v148 offset:39184
	ds_read_b128 v[158:161], v147 offset:4624
	ds_read_b128 v[162:165], v147 offset:6928
	ds_read_b128 v[174:177], v148 offset:41488
	ds_read_b128 v[178:181], v148 offset:43792
	s_waitcnt lgkmcnt(6)
	v_mfma_f32_16x16x32_bf16 v[50:53], v[166:169], v[150:153], v[50:53]
	s_waitcnt lgkmcnt(5)
	v_mfma_f32_16x16x32_bf16 v[54:57], v[166:169], v[154:157], v[54:57]
	s_waitcnt lgkmcnt(4)
	v_mfma_f32_16x16x32_bf16 v[58:61], v[170:173], v[150:153], v[58:61]
	v_mfma_f32_16x16x32_bf16 v[62:65], v[170:173], v[154:157], v[62:65]
	ds_read_b128 v[214:217], v148 offset:36944
	ds_read_b128 v[198:201], v147 offset:80
	ds_read_b128 v[202:205], v147 offset:2384
	ds_read_b128 v[218:221], v148 offset:39248
	s_waitcnt lgkmcnt(7)
	v_mfma_f32_16x16x32_bf16 v[18:21], v[166:169], v[158:161], v[18:21]
	v_mfma_f32_16x16x32_bf16 v[26:29], v[170:173], v[158:161], v[26:29]
	s_waitcnt lgkmcnt(6)
	v_mfma_f32_16x16x32_bf16 v[22:25], v[166:169], v[162:165], v[22:25]
	v_mfma_f32_16x16x32_bf16 v[30:33], v[170:173], v[162:165], v[30:33]
	ds_read_b128 v[206:209], v147 offset:4688
	ds_read_b128 v[210:213], v147 offset:6992
	ds_read_b128 v[222:225], v148 offset:41552
	ds_read_b128 v[226:229], v148 offset:43856
	s_waitcnt lgkmcnt(9)
	v_mfma_f32_16x16x32_bf16 v[34:37], v[174:177], v[150:153], v[34:37]
	v_mfma_f32_16x16x32_bf16 v[38:41], v[174:177], v[154:157], v[38:41]
	v_mfma_f32_16x16x32_bf16 v[2:5], v[174:177], v[158:161], v[2:5]
	v_mfma_f32_16x16x32_bf16 v[6:9], v[174:177], v[162:165], v[6:9]
	s_waitcnt lgkmcnt(8)
	v_mfma_f32_16x16x32_bf16 v[42:45], v[178:181], v[150:153], v[42:45]
	v_mfma_f32_16x16x32_bf16 v[46:49], v[178:181], v[154:157], v[46:49]
	s_waitcnt vmcnt(14)
	ds_write_b128 v144, v[98:101] offset:18448
	ds_write_b128 v144, v[102:105] offset:55312
	v_mfma_f32_16x16x32_bf16 v[10:13], v[178:181], v[158:161], v[10:13]
	v_mfma_f32_16x16x32_bf16 v[14:17], v[178:181], v[162:165], v[14:17]
	s_waitcnt lgkmcnt(8)
	v_mfma_f32_16x16x32_bf16 v[50:53], v[214:217], v[198:201], v[50:53]
	s_waitcnt lgkmcnt(7)
	v_mfma_f32_16x16x32_bf16 v[54:57], v[214:217], v[202:205], v[54:57]
	s_waitcnt vmcnt(12)
	ds_write_b128 v144, v[106:109] offset:23056
	ds_write_b128 v144, v[110:113] offset:59920
	s_waitcnt lgkmcnt(8)
	v_mfma_f32_16x16x32_bf16 v[58:61], v[218:221], v[198:201], v[58:61]
	v_mfma_f32_16x16x32_bf16 v[62:65], v[218:221], v[202:205], v[62:65]
	s_waitcnt lgkmcnt(7)
	v_mfma_f32_16x16x32_bf16 v[18:21], v[214:217], v[206:209], v[18:21]
	v_mfma_f32_16x16x32_bf16 v[26:29], v[218:221], v[206:209], v[26:29]
	s_waitcnt vmcnt(10)
	ds_write_b128 v144, v[114:117] offset:27664
	ds_write_b128 v144, v[118:121] offset:64528
	s_waitcnt lgkmcnt(8)
	v_mfma_f32_16x16x32_bf16 v[22:25], v[214:217], v[210:213], v[22:25]
	v_mfma_f32_16x16x32_bf16 v[30:33], v[218:221], v[210:213], v[30:33]
	s_waitcnt lgkmcnt(7)
	v_mfma_f32_16x16x32_bf16 v[34:37], v[222:225], v[198:201], v[34:37]
	v_mfma_f32_16x16x32_bf16 v[38:41], v[222:225], v[202:205], v[38:41]
	s_waitcnt vmcnt(8)
	ds_write_b128 v144, v[122:125] offset:32272
	ds_write_b128 v145, v[126:129] offset:32256
	v_mfma_f32_16x16x32_bf16 v[2:5], v[222:225], v[206:209], v[2:5]
	v_mfma_f32_16x16x32_bf16 v[6:9], v[222:225], v[210:213], v[6:9]
	s_waitcnt lgkmcnt(8)
	v_mfma_f32_16x16x32_bf16 v[42:45], v[226:229], v[198:201], v[42:45]
	v_mfma_f32_16x16x32_bf16 v[46:49], v[226:229], v[202:205], v[46:49]
	v_mfma_f32_16x16x32_bf16 v[10:13], v[226:229], v[206:209], v[10:13]
	v_mfma_f32_16x16x32_bf16 v[14:17], v[226:229], v[210:213], v[14:17]
	s_waitcnt lgkmcnt(0)
	s_barrier
	s_sleep 1
	global_load_dwordx4 v[98:101], v194, s[100:101] offset:384
	global_load_dwordx4 v[102:105], v190, s[98:99] offset:384
	global_load_dwordx4 v[106:109], v195, s[100:101] offset:384
	global_load_dwordx4 v[110:113], v191, s[98:99] offset:384
	global_load_dwordx4 v[114:117], v196, s[100:101] offset:384
	global_load_dwordx4 v[118:121], v192, s[98:99] offset:384
	global_load_dwordx4 v[122:125], v197, s[100:101] offset:384
	global_load_dwordx4 v[126:129], v193, s[98:99] offset:384
	ds_read_b128 v[166:169], v148 offset:55312
	ds_read_b128 v[150:153], v147 offset:18448
	ds_read_b128 v[154:157], v147 offset:20752
	ds_read_b128 v[170:173], v148 offset:57616
	ds_read_b128 v[158:161], v147 offset:23056
	ds_read_b128 v[162:165], v147 offset:25360
	ds_read_b128 v[174:177], v148 offset:59920
	ds_read_b128 v[178:181], v148 offset:62224
	s_waitcnt lgkmcnt(6)
	v_mfma_f32_16x16x32_bf16 v[50:53], v[166:169], v[150:153], v[50:53]
	s_waitcnt lgkmcnt(5)
	v_mfma_f32_16x16x32_bf16 v[54:57], v[166:169], v[154:157], v[54:57]
	s_waitcnt lgkmcnt(4)
	v_mfma_f32_16x16x32_bf16 v[58:61], v[170:173], v[150:153], v[58:61]
	v_mfma_f32_16x16x32_bf16 v[62:65], v[170:173], v[154:157], v[62:65]
	ds_read_b128 v[214:217], v148 offset:55376
	ds_read_b128 v[198:201], v147 offset:18512
	ds_read_b128 v[202:205], v147 offset:20816
	ds_read_b128 v[218:221], v148 offset:57680
	s_waitcnt lgkmcnt(7)
	v_mfma_f32_16x16x32_bf16 v[18:21], v[166:169], v[158:161], v[18:21]
	v_mfma_f32_16x16x32_bf16 v[26:29], v[170:173], v[158:161], v[26:29]
	s_waitcnt lgkmcnt(6)
; template <bool SWAP, class Epi>
; DI void gemm_tile(const u16* __restrict__ A, int lda, const u16* __restrict__ Bt, int ldb, int K, int m0, int n0, char* smem, Epi&& epi) {
;     ...
;   for (int kt = 0; kt < KT; kt += 2) {
;     if (kt + 2 < KT) {
;       const int k0 = (kt + 2) << 6;
; #pragma unroll
;       for (int i = 0; i < 4; ++i) { ra0[i] = *(const u32x4*)(ag + (size_t)i * 32 * lda + k0); rb0[i] = *(const u32x4*)(bg + (size_t)i * 32 * ldb + k0); }
;     }
;     compute(0);
; #pragma unroll
;     for (int i = 0; i < 4; ++i) { *(u32x4*)(asw + 128 * 72 + 32 * i * 72) = ra1[i]; *(u32x4*)(bsw + 128 * 72 + 32 * i * 72) = rb1[i]; }
;     __syncthreads();
;     if (kt + 3 < KT) {
;       const int k0 = (kt + 3) << 6;
; #pragma unroll
;       for (int i = 0; i < 4; ++i) { ra1[i] = *(const u32x4*)(ag + (size_t)i * 32 * lda + k0); rb1[i] = *(const u32x4*)(bg + (size_t)i * 32 * ldb + k0); }
;     }
;     compute(1);
;     if (kt + 2 < KT) {
; #pragma unroll
;       for (int i = 0; i < 4; ++i) { *(u32x4*)(asw + 32 * i * 72) = ra0[i]; *(u32x4*)(bsw + 32 * i * 72) = rb0[i]; }
;     }
;     __syncthreads();
;   }
	v_mfma_f32_16x16x32_bf16 v[22:25], v[166:169], v[162:165], v[22:25]
	v_mfma_f32_16x16x32_bf16 v[30:33], v[170:173], v[162:165], v[30:33]
	ds_read_b128 v[206:209], v147 offset:23120
	ds_read_b128 v[210:213], v147 offset:25424
	ds_read_b128 v[222:225], v148 offset:59984
	ds_read_b128 v[226:229], v148 offset:62288
	s_waitcnt lgkmcnt(9)
	v_mfma_f32_16x16x32_bf16 v[34:37], v[174:177], v[150:153], v[34:37]
	v_mfma_f32_16x16x32_bf16 v[38:41], v[174:177], v[154:157], v[38:41]
	v_mfma_f32_16x16x32_bf16 v[2:5], v[174:177], v[158:161], v[2:5]
	v_mfma_f32_16x16x32_bf16 v[6:9], v[174:177], v[162:165], v[6:9]
	s_waitcnt lgkmcnt(8)
	v_mfma_f32_16x16x32_bf16 v[42:45], v[178:181], v[150:153], v[42:45]
	v_mfma_f32_16x16x32_bf16 v[46:49], v[178:181], v[154:157], v[46:49]
	s_waitcnt vmcnt(14)
	ds_write_b128 v144, v[66:69] offset:16
	ds_write_b128 v144, v[70:73] offset:36880
	v_mfma_f32_16x16x32_bf16 v[10:13], v[178:181], v[158:161], v[10:13]
	v_mfma_f32_16x16x32_bf16 v[14:17], v[178:181], v[162:165], v[14:17]
	s_waitcnt lgkmcnt(8)
	v_mfma_f32_16x16x32_bf16 v[50:53], v[214:217], v[198:201], v[50:53]
	s_waitcnt lgkmcnt(7)
	v_mfma_f32_16x16x32_bf16 v[54:57], v[214:217], v[202:205], v[54:57]
	s_waitcnt vmcnt(12)
	ds_write_b128 v144, v[74:77] offset:4624
	ds_write_b128 v144, v[78:81] offset:41488
	s_waitcnt lgkmcnt(8)
	v_mfma_f32_16x16x32_bf16 v[58:61], v[218:221], v[198:201], v[58:61]
	v_mfma_f32_16x16x32_bf16 v[62:65], v[218:221], v[202:205], v[62:65]
	s_waitcnt lgkmcnt(7)
	v_mfma_f32_16x16x32_bf16 v[18:21], v[214:217], v[206:209], v[18:21]
	v_mfma_f32_16x16x32_bf16 v[26:29], v[218:221], v[206:209], v[26:29]
	s_waitcnt vmcnt(10)
	ds_write_b128 v144, v[82:85] offset:9232
	ds_write_b128 v144, v[86:89] offset:46096
	s_waitcnt lgkmcnt(8)
	v_mfma_f32_16x16x32_bf16 v[22:25], v[214:217], v[210:213], v[22:25]
	v_mfma_f32_16x16x32_bf16 v[30:33], v[218:221], v[210:213], v[30:33]
	s_waitcnt lgkmcnt(7)
	v_mfma_f32_16x16x32_bf16 v[34:37], v[222:225], v[198:201], v[34:37]
	v_mfma_f32_16x16x32_bf16 v[38:41], v[222:225], v[202:205], v[38:41]
	s_waitcnt vmcnt(8)
	ds_write_b128 v144, v[90:93] offset:13840
	ds_write_b128 v144, v[94:97] offset:50704
	v_mfma_f32_16x16x32_bf16 v[2:5], v[222:225], v[206:209], v[2:5]
	v_mfma_f32_16x16x32_bf16 v[6:9], v[222:225], v[210:213], v[6:9]
	s_waitcnt lgkmcnt(8)
	v_mfma_f32_16x16x32_bf16 v[42:45], v[226:229], v[198:201], v[42:45]
	v_mfma_f32_16x16x32_bf16 v[46:49], v[226:229], v[202:205], v[46:49]
	v_mfma_f32_16x16x32_bf16 v[10:13], v[226:229], v[206:209], v[10:13]
	v_mfma_f32_16x16x32_bf16 v[14:17], v[226:229], v[210:213], v[14:17]
	s_add_i32 s18, s18, 2
	s_add_u32 s98, s98, 256
	s_addc_u32 s99, s99, 0
	s_add_u32 s100, s100, 256
	s_addc_u32 s101, s101, 0
	s_waitcnt lgkmcnt(0)
	s_barrier
	s_cmp_lt_u32 s18, 30
	s_cbranch_scc1 .LBB0_955
	ds_read_b128 v[166:169], v148 offset:36880
	ds_read_b128 v[150:153], v147 offset:16
	ds_read_b128 v[154:157], v147 offset:2320
	ds_read_b128 v[170:173], v148 offset:39184
	ds_read_b128 v[158:161], v147 offset:4624
	ds_read_b128 v[162:165], v147 offset:6928
	ds_read_b128 v[174:177], v148 offset:41488
	ds_read_b128 v[178:181], v148 offset:43792
	s_waitcnt lgkmcnt(6)
	v_mfma_f32_16x16x32_bf16 v[50:53], v[166:169], v[150:153], v[50:53]
	s_waitcnt lgkmcnt(5)
	v_mfma_f32_16x16x32_bf16 v[54:57], v[166:169], v[154:157], v[54:57]
	s_waitcnt lgkmcnt(4)
	v_mfma_f32_16x16x32_bf16 v[58:61], v[170:173], v[150:153], v[58:61]
	v_mfma_f32_16x16x32_bf16 v[62:65], v[170:173], v[154:157], v[62:65]
	ds_read_b128 v[214:217], v148 offset:36944
	ds_read_b128 v[198:201], v147 offset:80
	ds_read_b128 v[202:205], v147 offset:2384
	ds_read_b128 v[218:221], v148 offset:39248
	s_waitcnt lgkmcnt(7)
	v_mfma_f32_16x16x32_bf16 v[18:21], v[166:169], v[158:161], v[18:21]
	v_mfma_f32_16x16x32_bf16 v[26:29], v[170:173], v[158:161], v[26:29]
	s_waitcnt lgkmcnt(6)
	v_mfma_f32_16x16x32_bf16 v[22:25], v[166:169], v[162:165], v[22:25]
	v_mfma_f32_16x16x32_bf16 v[30:33], v[170:173], v[162:165], v[30:33]
	ds_read_b128 v[206:209], v147 offset:4688
	ds_read_b128 v[210:213], v147 offset:6992
	ds_read_b128 v[222:225], v148 offset:41552
	ds_read_b128 v[226:229], v148 offset:43856
	s_waitcnt lgkmcnt(9)
	v_mfma_f32_16x16x32_bf16 v[34:37], v[174:177], v[150:153], v[34:37]
	v_mfma_f32_16x16x32_bf16 v[38:41], v[174:177], v[154:157], v[38:41]
	v_mfma_f32_16x16x32_bf16 v[2:5], v[174:177], v[158:161], v[2:5]
	v_mfma_f32_16x16x32_bf16 v[6:9], v[174:177], v[162:165], v[6:9]
	s_waitcnt lgkmcnt(8)
	v_mfma_f32_16x16x32_bf16 v[42:45], v[178:181], v[150:153], v[42:45]
	v_mfma_f32_16x16x32_bf16 v[46:49], v[178:181], v[154:157], v[46:49]
	s_waitcnt vmcnt(6)
	ds_write_b128 v144, v[98:101] offset:18448
	ds_write_b128 v144, v[102:105] offset:55312
	v_mfma_f32_16x16x32_bf16 v[10:13], v[178:181], v[158:161], v[10:13]
	v_mfma_f32_16x16x32_bf16 v[14:17], v[178:181], v[162:165], v[14:17]
	s_waitcnt lgkmcnt(8)
	v_mfma_f32_16x16x32_bf16 v[50:53], v[214:217], v[198:201], v[50:53]
	s_waitcnt lgkmcnt(7)
	v_mfma_f32_16x16x32_bf16 v[54:57], v[214:217], v[202:205], v[54:57]
	s_waitcnt vmcnt(4)
	ds_write_b128 v144, v[106:109] offset:23056
	ds_write_b128 v144, v[110:113] offset:59920
	s_waitcnt lgkmcnt(8)
	v_mfma_f32_16x16x32_bf16 v[58:61], v[218:221], v[198:201], v[58:61]
	v_mfma_f32_16x16x32_bf16 v[62:65], v[218:221], v[202:205], v[62:65]
	s_waitcnt lgkmcnt(7)
	v_mfma_f32_16x16x32_bf16 v[18:21], v[214:217], v[206:209], v[18:21]
	v_mfma_f32_16x16x32_bf16 v[26:29], v[218:221], v[206:209], v[26:29]
	s_waitcnt vmcnt(2)
	ds_write_b128 v144, v[114:117] offset:27664
	ds_write_b128 v144, v[118:121] offset:64528
	s_waitcnt lgkmcnt(8)
	v_mfma_f32_16x16x32_bf16 v[22:25], v[214:217], v[210:213], v[22:25]
	v_mfma_f32_16x16x32_bf16 v[30:33], v[218:221], v[210:213], v[30:33]
	s_waitcnt lgkmcnt(7)
	v_mfma_f32_16x16x32_bf16 v[34:37], v[222:225], v[198:201], v[34:37]
	v_mfma_f32_16x16x32_bf16 v[38:41], v[222:225], v[202:205], v[38:41]
	s_waitcnt vmcnt(0)
	ds_write_b128 v144, v[122:125] offset:32272
	ds_write_b128 v145, v[126:129] offset:32256
	v_mfma_f32_16x16x32_bf16 v[2:5], v[222:225], v[206:209], v[2:5]
	v_mfma_f32_16x16x32_bf16 v[6:9], v[222:225], v[210:213], v[6:9]
	s_waitcnt lgkmcnt(8)
	v_mfma_f32_16x16x32_bf16 v[42:45], v[226:229], v[198:201], v[42:45]
	v_mfma_f32_16x16x32_bf16 v[46:49], v[226:229], v[202:205], v[46:49]
	v_mfma_f32_16x16x32_bf16 v[10:13], v[226:229], v[206:209], v[10:13]
	v_mfma_f32_16x16x32_bf16 v[14:17], v[226:229], v[210:213], v[14:17]
	s_waitcnt lgkmcnt(0)
	s_barrier
; #define MFMA(a, b, c) __builtin_amdgcn_mfma_f32_32x32x16_bf16((a), (b), (c), 0, 0, 0)
; template <bool SWAP, class Epi>
; DI void gemm_tile(const u16* __restrict__ A, int lda, const u16* __restrict__ Bt, int ldb, int K, int m0, int n0, char* smem, Epi&& epi) {
;     ...
;   auto compute = [&](int buf) __attribute__((always_inline)) {
;     bf16x8 af[2][2], bfr[2][2];
;     af[0][0] = *(const bf16x8*)(Asb + buf * 128 * 72);
;     af[0][1] = *(const bf16x8*)(Asb + buf * 128 * 72 + 32 * 72);
;     bfr[0][0] = *(const bf16x8*)(Bsb + buf * 128 * 72);
;     bfr[0][1] = *(const bf16x8*)(Bsb + buf * 128 * 72 + 32 * 72);
; #pragma unroll
;     for (int ks = 0; ks < 4; ++ks) {
;       const int c = ks & 1, n = c ^ 1;
;       if (ks < 3) {
;         af[n][0] = *(const bf16x8*)(Asb + buf * 128 * 72 + (ks + 1) * 16);
;         af[n][1] = *(const bf16x8*)(Asb + buf * 128 * 72 + 32 * 72 + (ks + 1) * 16);
;         bfr[n][0] = *(const bf16x8*)(Bsb + buf * 128 * 72 + (ks + 1) * 16);
;         bfr[n][1] = *(const bf16x8*)(Bsb + buf * 128 * 72 + 32 * 72 + (ks + 1) * 16);
;       }
;       __builtin_amdgcn_sched_barrier(0);
; #pragma unroll
;       for (int mi = 0; mi < 2; ++mi)
; #pragma unroll
;         for (int ni = 0; ni < 2; ++ni) {
;           if (SWAP) acc[mi][ni] = MFMA(bfr[c][ni], af[c][mi], acc[mi][ni]);
;           else acc[mi][ni] = MFMA(af[c][mi], bfr[c][ni], acc[mi][ni]);
;         }
;       __builtin_amdgcn_sched_barrier(0);
;     }
;   };
;     ...
;     compute(1);
;     if (kt + 2 < KT) {
; #pragma unroll
;       for (int i = 0; i < 4; ++i) { *(u32x4*)(asw + 32 * i * 72) = ra0[i]; *(u32x4*)(bsw + 32 * i * 72) = rb0[i]; }
;     }
;     __syncthreads();
;   }
;   epi(acc, m0 + wm * 64, n0 + wn * 64, r, hi);
	ds_read_b128 v[166:169], v148 offset:55312
	ds_read_b128 v[150:153], v147 offset:18448
	ds_read_b128 v[154:157], v147 offset:20752
	ds_read_b128 v[170:173], v148 offset:57616
	ds_read_b128 v[158:161], v147 offset:23056
	ds_read_b128 v[162:165], v147 offset:25360
	ds_read_b128 v[174:177], v148 offset:59920
	ds_read_b128 v[178:181], v148 offset:62224
	s_waitcnt lgkmcnt(6)
	v_mfma_f32_16x16x32_bf16 v[50:53], v[166:169], v[150:153], v[50:53]
	s_waitcnt lgkmcnt(5)
	v_mfma_f32_16x16x32_bf16 v[54:57], v[166:169], v[154:157], v[54:57]
	s_waitcnt lgkmcnt(4)
	v_mfma_f32_16x16x32_bf16 v[58:61], v[170:173], v[150:153], v[58:61]
	v_mfma_f32_16x16x32_bf16 v[62:65], v[170:173], v[154:157], v[62:65]
	ds_read_b128 v[214:217], v148 offset:55376
	ds_read_b128 v[198:201], v147 offset:18512
	ds_read_b128 v[202:205], v147 offset:20816
	ds_read_b128 v[218:221], v148 offset:57680
	s_waitcnt lgkmcnt(7)
	v_mfma_f32_16x16x32_bf16 v[18:21], v[166:169], v[158:161], v[18:21]
	v_mfma_f32_16x16x32_bf16 v[26:29], v[170:173], v[158:161], v[26:29]
	s_waitcnt lgkmcnt(6)
	v_mfma_f32_16x16x32_bf16 v[22:25], v[166:169], v[162:165], v[22:25]
	v_mfma_f32_16x16x32_bf16 v[30:33], v[170:173], v[162:165], v[30:33]
	ds_read_b128 v[206:209], v147 offset:23120
	ds_read_b128 v[210:213], v147 offset:25424
	ds_read_b128 v[222:225], v148 offset:59984
	ds_read_b128 v[226:229], v148 offset:62288
	s_waitcnt lgkmcnt(9)
	v_mfma_f32_16x16x32_bf16 v[34:37], v[174:177], v[150:153], v[34:37]
	v_mfma_f32_16x16x32_bf16 v[38:41], v[174:177], v[154:157], v[38:41]
	v_mfma_f32_16x16x32_bf16 v[2:5], v[174:177], v[158:161], v[2:5]
	v_mfma_f32_16x16x32_bf16 v[6:9], v[174:177], v[162:165], v[6:9]
	s_waitcnt lgkmcnt(8)
	v_mfma_f32_16x16x32_bf16 v[42:45], v[178:181], v[150:153], v[42:45]
	v_mfma_f32_16x16x32_bf16 v[46:49], v[178:181], v[154:157], v[46:49]
	v_mfma_f32_16x16x32_bf16 v[10:13], v[178:181], v[158:161], v[10:13]
	v_mfma_f32_16x16x32_bf16 v[14:17], v[178:181], v[162:165], v[14:17]
	s_waitcnt lgkmcnt(6)
	v_mfma_f32_16x16x32_bf16 v[50:53], v[214:217], v[198:201], v[50:53]
	s_waitcnt lgkmcnt(5)
	v_mfma_f32_16x16x32_bf16 v[54:57], v[214:217], v[202:205], v[54:57]
	s_waitcnt lgkmcnt(4)
	v_mfma_f32_16x16x32_bf16 v[58:61], v[218:221], v[198:201], v[58:61]
	v_mfma_f32_16x16x32_bf16 v[62:65], v[218:221], v[202:205], v[62:65]
	s_waitcnt lgkmcnt(3)
	v_mfma_f32_16x16x32_bf16 v[18:21], v[214:217], v[206:209], v[18:21]
	v_mfma_f32_16x16x32_bf16 v[26:29], v[218:221], v[206:209], v[26:29]
	s_waitcnt lgkmcnt(2)
	v_mfma_f32_16x16x32_bf16 v[22:25], v[214:217], v[210:213], v[22:25]
	v_mfma_f32_16x16x32_bf16 v[30:33], v[218:221], v[210:213], v[30:33]
	s_waitcnt lgkmcnt(1)
	v_mfma_f32_16x16x32_bf16 v[34:37], v[222:225], v[198:201], v[34:37]
	v_mfma_f32_16x16x32_bf16 v[38:41], v[222:225], v[202:205], v[38:41]
	v_mfma_f32_16x16x32_bf16 v[2:5], v[222:225], v[206:209], v[2:5]
	v_mfma_f32_16x16x32_bf16 v[6:9], v[222:225], v[210:213], v[6:9]
	s_waitcnt lgkmcnt(0)
	v_mfma_f32_16x16x32_bf16 v[42:45], v[226:229], v[198:201], v[42:45]
	v_mfma_f32_16x16x32_bf16 v[46:49], v[226:229], v[202:205], v[46:49]
	v_mfma_f32_16x16x32_bf16 v[10:13], v[226:229], v[206:209], v[10:13]
	v_mfma_f32_16x16x32_bf16 v[14:17], v[226:229], v[210:213], v[14:17]
	s_nop 7
	s_nop 7
	v_permlane16_swap_b32_e32 v50, v54
	v_permlane16_swap_b32_e32 v51, v55
	v_permlane16_swap_b32_e32 v52, v56
	v_permlane16_swap_b32_e32 v53, v57
	v_permlane16_swap_b32_e32 v58, v62
	v_permlane16_swap_b32_e32 v59, v63
	v_permlane16_swap_b32_e32 v60, v64
	v_permlane16_swap_b32_e32 v61, v65
	v_permlane16_swap_b32_e32 v34, v38
	v_permlane16_swap_b32_e32 v35, v39
	v_permlane16_swap_b32_e32 v36, v40
	v_permlane16_swap_b32_e32 v37, v41
	v_permlane16_swap_b32_e32 v42, v46
	v_permlane16_swap_b32_e32 v43, v47
	v_permlane16_swap_b32_e32 v44, v48
	v_permlane16_swap_b32_e32 v45, v49
	v_permlane16_swap_b32_e32 v18, v22
	v_permlane16_swap_b32_e32 v19, v23
	v_permlane16_swap_b32_e32 v20, v24
	v_permlane16_swap_b32_e32 v21, v25
	v_permlane16_swap_b32_e32 v26, v30
	v_permlane16_swap_b32_e32 v27, v31
	v_permlane16_swap_b32_e32 v28, v32
	v_permlane16_swap_b32_e32 v29, v33
	v_permlane16_swap_b32_e32 v2, v6
	v_permlane16_swap_b32_e32 v3, v7
	v_permlane16_swap_b32_e32 v4, v8
	v_permlane16_swap_b32_e32 v5, v9
	v_permlane16_swap_b32_e32 v10, v14
	v_permlane16_swap_b32_e32 v11, v15
	v_permlane16_swap_b32_e32 v12, v16
	v_permlane16_swap_b32_e32 v13, v17
	s_waitcnt lgkmcnt(0)
	s_barrier
	s_branch .LBB0_952
